# attention PV sections: per-MFMA counted lgkmcnt waits (6, last group 6/4/2/0) instead of a full LDS-queue drain before every group of four
# baseline (speedup 1.0000x reference)
; __device__ __forceinline__ void finishSM(f32x16& p0, f32x16& p1, float alpha, float& l_reg, bf16x8& pa0, bf16x8& pa1, bf16x8& pa2, bf16x8& pa3) {
;     for (int r = 0; r < 16; ++r) p1[r] = __builtin_amdgcn_exp2f(p1[r]);
;     float ps = 0; for (int r = 0; r < 16; ++r) ps += p0[r]; for (int r = 0; r < 16; ++r) ps += p1[r];
;     { auto rr = __builtin_amdgcn_permlane32_swap(__float_as_uint(ps), __float_as_uint(ps), false, false);
;       ps = __uint_as_float(rr[0]) + __uint_as_float(rr[1]); }
;     l_reg = l_reg * alpha + ps;
;     ...
;     PK4(p0, 0, pa0); PK4(p0, 8, pa1); PK4(p1, 0, pa2); PK4(p1, 8, pa3);
;     ...
; }
; template <int KB>
; __device__ __forceinline__ void qkt(f32x16& p0, f32x16& p1, const char* K_lds, int r32, int hi, const bf16x8* qr) {
;     p0 = f32x16{}; p1 = f32x16{};
;     const char* kb[4];
; #pragma unroll
;     for (int dd = 0; dd < 4; ++dd) kb[dd] = K_lds + KB * SHM_K + KSWZ(r32, (dd * 16 + hi * 8) * 2);
; #pragma unroll
;     for (int d0 = 0; d0 < 8; ++d0) { const char* a = kb[d0 & 3] + (d0 >> 2) * 128;
;         bf16x8 b0 = *reinterpret_cast<const bf16x8*>(a);
;         bf16x8 b1 = *reinterpret_cast<const bf16x8*>(a + 32 * 256);
;         p0 = __builtin_amdgcn_mfma_f32_32x32x16_bf16(b0, qr[d0], p0, 0, 0, 0);
;         p1 = __builtin_amdgcn_mfma_f32_32x32x16_bf16(b1, qr[d0], p1, 0, 0, 0); }
; }
.LBB0_89:
	ds_read_b128 v[66:69], v169 offset:49152
	ds_read_b128 v[70:73], v169 offset:57344
	ds_read_b128 v[100:103], v193 offset:49152
	ds_read_b128 v[136:139], v193 offset:57344
	ds_read_b128 v[234:237], v194 offset:49152
	ds_read_b128 v[238:241], v194 offset:57344
	v_add_f32_e32 v148, 0, v231
	v_add_f32_e32 v148, v233, v148
	v_add_f32_e32 v148, v229, v148
	v_add_f32_e32 v148, v232, v148
	v_add_f32_e32 v148, v228, v148
	v_add_f32_e32 v148, v230, v148
	v_add_f32_e32 v148, v226, v148
	v_add_f32_e32 v148, v227, v148
	v_add_f32_e32 v148, v223, v148
	v_add_f32_e32 v148, v225, v148
	v_add_f32_e32 v148, v209, v148
	v_add_f32_e32 v148, v224, v148
	v_add_f32_e32 v148, v206, v148
	v_add_f32_e32 v148, v208, v148
	v_add_f32_e32 v148, v205, v148
	v_add_f32_e32 v148, v207, v148
	v_exp_f32_e32 v140, v152
	v_exp_f32_e32 v141, v153
	v_exp_f32_e32 v142, v180
	v_exp_f32_e32 v143, v181
	s_waitcnt lgkmcnt(5)
	v_mfma_f32_32x32x16_bf16 v[82:97], v[66:69], v[132:135], 0
	v_exp_f32_e32 v144, v160
	v_exp_f32_e32 v145, v161
	v_exp_f32_e32 v146, v154
	v_exp_f32_e32 v147, v155
	s_waitcnt lgkmcnt(4)
	v_mfma_f32_32x32x16_bf16 v[66:81], v[70:73], v[132:135], 0
	v_exp_f32_e32 v178, v178
	v_exp_f32_e32 v179, v179
	v_exp_f32_e32 v162, v162
	v_exp_f32_e32 v163, v163
	s_waitcnt lgkmcnt(3)
	v_mfma_f32_32x32x16_bf16 v[82:97], v[100:103], v[128:131], v[82:97]
	v_add_f32_e32 v148, v178, v148
	v_add_f32_e32 v148, v179, v148
	v_add_f32_e32 v148, v162, v148
	v_exp_f32_e32 v158, v158
	s_waitcnt lgkmcnt(2)
	v_mfma_f32_32x32x16_bf16 v[66:81], v[136:139], v[128:131], v[66:81]
	v_exp_f32_e32 v159, v159
	v_exp_f32_e32 v156, v156
	v_exp_f32_e32 v157, v157
	v_add_f32_e32 v148, v163, v148
	ds_read_b128 v[100:103], v195 offset:49152
	ds_read_b128 v[136:139], v195 offset:57344
	s_waitcnt lgkmcnt(3)
	v_mfma_f32_32x32x16_bf16 v[82:97], v[234:237], v[124:127], v[82:97]
	v_add_f32_e32 v148, v158, v148
	v_add_f32_e32 v148, v159, v148
	v_add_f32_e32 v148, v156, v148
	v_add_f32_e32 v148, v157, v148
	s_waitcnt lgkmcnt(2)
	v_mfma_f32_32x32x16_bf16 v[66:81], v[238:241], v[124:127], v[66:81]
	v_add_f32_e32 v148, v140, v148
	v_add_f32_e32 v148, v141, v148
	v_add_f32_e32 v148, v142, v148
	v_add_f32_e32 v148, v143, v148
	ds_read_b128 v[234:237], v169 offset:49280
	ds_read_b128 v[238:241], v169 offset:57472
	s_waitcnt lgkmcnt(3)
	v_mfma_f32_32x32x16_bf16 v[82:97], v[100:103], v[120:123], v[82:97]
	v_add_f32_e32 v148, v144, v148
	v_add_f32_e32 v148, v145, v148
	v_add_f32_e32 v148, v146, v148
	v_add_f32_e32 v199, v147, v148
	s_waitcnt lgkmcnt(2)
	v_mfma_f32_32x32x16_bf16 v[66:81], v[136:139], v[120:123], v[66:81]
	v_mov_b32_e32 v200, v199
	s_nop 1
	v_permlane32_swap_b32_e32 v199, v200
	v_cvt_pk_bf16_f32 v148, v231, v233
	v_cvt_pk_bf16_f32 v149, v229, v232
	v_cvt_pk_bf16_f32 v150, v228, v230
	ds_read_b128 v[100:103], v193 offset:49280
	ds_read_b128 v[136:139], v193 offset:57472
	s_waitcnt lgkmcnt(3)
	v_mfma_f32_32x32x16_bf16 v[82:97], v[234:237], v[116:119], v[82:97]
	v_cvt_pk_bf16_f32 v151, v226, v227
	v_cvt_pk_bf16_f32 v152, v223, v225
	v_cvt_pk_bf16_f32 v153, v209, v224
	s_waitcnt lgkmcnt(2)
	v_mfma_f32_32x32x16_bf16 v[66:81], v[238:241], v[116:119], v[66:81]
	v_cvt_pk_bf16_f32 v154, v206, v208
	v_cvt_pk_bf16_f32 v155, v205, v207
	v_cvt_pk_bf16_f32 v158, v158, v159
	ds_read_b128 v[234:237], v194 offset:49280
	ds_read_b128 v[238:241], v194 offset:57472
	s_waitcnt lgkmcnt(3)
	v_mfma_f32_32x32x16_bf16 v[82:97], v[100:103], v[112:115], v[82:97]
	v_cvt_pk_bf16_f32 v159, v156, v157
	v_cvt_pk_bf16_f32 v156, v178, v179
	v_cvt_pk_bf16_f32 v157, v162, v163
	s_waitcnt lgkmcnt(2)
	v_mfma_f32_32x32x16_bf16 v[66:81], v[136:139], v[112:115], v[66:81]
	v_cvt_pk_bf16_f32 v160, v140, v141
	v_cvt_pk_bf16_f32 v161, v142, v143
	v_cvt_pk_bf16_f32 v162, v144, v145
	ds_read_b128 v[100:103], v195 offset:49280
	ds_read_b128 v[136:139], v195 offset:57472
	ds_read_b64_tr_b16 v[172:173], v185 offset:0
	ds_read_b64_tr_b16 v[174:175], v185 offset:0x800
	ds_read_b64_tr_b16 v[202:203], v185 offset:0x1000
	ds_read_b64_tr_b16 v[204:205], v185 offset:0x1800
	ds_read_b64_tr_b16 v[206:207], v185 offset:0x2000
	ds_read_b64_tr_b16 v[208:209], v185 offset:0x2800
	ds_read_b64_tr_b16 v[224:225], v185 offset:0x3000
	ds_read_b64_tr_b16 v[226:227], v185 offset:0x3800
	s_waitcnt lgkmcnt(11)
	v_mfma_f32_32x32x16_bf16 v[82:97], v[234:237], v[108:111], v[82:97]
	v_cvt_pk_bf16_f32 v163, v146, v147
	s_nop 0
	v_permlane32_swap_b32_e32 v148, v150
	v_permlane32_swap_b32_e32 v149, v151
	s_waitcnt lgkmcnt(10)
	v_mfma_f32_32x32x16_bf16 v[66:81], v[238:241], v[108:111], v[66:81]
	v_permlane32_swap_b32_e32 v152, v154
	v_permlane32_swap_b32_e32 v153, v155
	v_permlane32_swap_b32_e32 v156, v158
	s_waitcnt lgkmcnt(9)
	v_mfma_f32_32x32x16_bf16 v[82:97], v[100:103], v[104:107], v[82:97]
	v_permlane32_swap_b32_e32 v157, v159
	v_permlane32_swap_b32_e32 v160, v162
	v_permlane32_swap_b32_e32 v161, v163
	s_waitcnt lgkmcnt(8)
	v_mfma_f32_32x32x16_bf16 v[66:81], v[136:139], v[104:107], v[66:81]
	v_add_u32_e32 v169, s100, v169
	v_add_u32_e32 v193, s100, v193
	v_add_u32_e32 v194, s100, v194
	v_add_u32_e32 v195, s100, v195
	s_sub_i32 s100, 0, s100
	s_sub_i32 m0, 0, s100
	s_max_i32 m0, m0, 0
	s_add_i32 m0, m0, s32
	s_add_i32 m0, m0, 0x4000
	s_nop 0
	global_load_lds_dwordx4 v[244:245], off
	s_add_i32 m0, m0, 0x2000
	s_nop 0
	global_load_lds_dwordx4 v[246:247], off
	v_lshl_add_u64 v[244:245], v[244:245], 0, v[250:251]
	v_lshl_add_u64 v[246:247], v[246:247], 0, v[250:251]
	s_sub_i32 m0, 0, s100
	s_max_i32 m0, m0, 0
	s_add_i32 m0, m0, s32
	s_add_i32 m0, m0, s32
	s_sub_i32 m0, m0, 0x10000
	s_nop 0
	global_load_lds_dwordx4 v[248:249], off
	s_add_i32 m0, m0, 896
	s_nop 0
	global_load_lds_dwordx4 v[248:249], off offset:128
	v_lshl_add_u64 v[248:249], v[248:249], 0, v[250:251]
	s_nop 0
	s_waitcnt lgkmcnt(6)
; __device__ __forceinline__ void mask_tile(f32x16& p0, f32x16& p1, int dq, unsigned W) {
;     const float NEG = -__builtin_inff();
; #pragma unroll
;     for (int r = 0; r < 16; ++r) {
;         const int c = (r & 3) + 8 * (r >> 2);
;         if ((unsigned)(dq - c) >= W) p0[r] = NEG;
;         if ((unsigned)(dq - c - 32) >= W) p1[r] = NEG;
;     }
; }
; template <int VB>
; __device__ __forceinline__ void pv_tile(f32x16* o, int vb0, bf16x8 pa0, bf16x8 pa1, bf16x8 pa2, bf16x8 pa3) {
;     ...
;     PV_D0(0); PV_D0(1); PV_D0(2); PV_D0(3);
;     ...
; }
	v_mfma_f32_32x32x16_bf16 v[50:65], v[148:151], v[172:175], v[50:65]
	ds_read_b64_tr_b16 v[172:173], v185 offset:0x200
	ds_read_b64_tr_b16 v[174:175], v185 offset:0xa00
	s_waitcnt lgkmcnt(6)
	v_mfma_f32_32x32x16_bf16 v[50:65], v[152:155], v[202:205], v[50:65]
	ds_read_b64_tr_b16 v[202:203], v185 offset:0x1200
	ds_read_b64_tr_b16 v[204:205], v185 offset:0x1a00
	s_waitcnt lgkmcnt(6)
	v_mfma_f32_32x32x16_bf16 v[50:65], v[156:159], v[206:209], v[50:65]
	ds_read_b64_tr_b16 v[206:207], v185 offset:0x2200
	ds_read_b64_tr_b16 v[208:209], v185 offset:0x2a00
	s_waitcnt lgkmcnt(6)
	v_mfma_f32_32x32x16_bf16 v[50:65], v[160:163], v[224:227], v[50:65]
	ds_read_b64_tr_b16 v[224:225], v185 offset:0x3200
	ds_read_b64_tr_b16 v[226:227], v185 offset:0x3a00
	s_waitcnt lgkmcnt(6)
	v_mfma_f32_32x32x16_bf16 v[34:49], v[148:151], v[172:175], v[34:49]
	ds_read_b64_tr_b16 v[172:173], v185 offset:0x400
	ds_read_b64_tr_b16 v[174:175], v185 offset:0xc00
	s_waitcnt lgkmcnt(6)
	v_mfma_f32_32x32x16_bf16 v[34:49], v[152:155], v[202:205], v[34:49]
	ds_read_b64_tr_b16 v[202:203], v185 offset:0x1400
	ds_read_b64_tr_b16 v[204:205], v185 offset:0x1c00
	s_waitcnt lgkmcnt(6)
	v_mfma_f32_32x32x16_bf16 v[34:49], v[156:159], v[206:209], v[34:49]
	ds_read_b64_tr_b16 v[206:207], v185 offset:0x2400
	ds_read_b64_tr_b16 v[208:209], v185 offset:0x2c00
	s_waitcnt lgkmcnt(6)
	v_mfma_f32_32x32x16_bf16 v[34:49], v[160:163], v[224:227], v[34:49]
	ds_read_b64_tr_b16 v[224:225], v185 offset:0x3400
	ds_read_b64_tr_b16 v[226:227], v185 offset:0x3c00
	s_waitcnt lgkmcnt(6)
	v_mfma_f32_32x32x16_bf16 v[18:33], v[148:151], v[172:175], v[18:33]
	ds_read_b64_tr_b16 v[172:173], v185 offset:0x600
	ds_read_b64_tr_b16 v[174:175], v185 offset:0xe00
	s_waitcnt lgkmcnt(6)
	v_mfma_f32_32x32x16_bf16 v[18:33], v[152:155], v[202:205], v[18:33]
	ds_read_b64_tr_b16 v[202:203], v185 offset:0x1600
	ds_read_b64_tr_b16 v[204:205], v185 offset:0x1e00
	s_waitcnt lgkmcnt(6)
	v_mfma_f32_32x32x16_bf16 v[18:33], v[156:159], v[206:209], v[18:33]
	ds_read_b64_tr_b16 v[206:207], v185 offset:0x2600
	ds_read_b64_tr_b16 v[208:209], v185 offset:0x2e00
	s_waitcnt lgkmcnt(6)
	v_mfma_f32_32x32x16_bf16 v[18:33], v[160:163], v[224:227], v[18:33]
	ds_read_b64_tr_b16 v[224:225], v185 offset:0x3600
	ds_read_b64_tr_b16 v[226:227], v185 offset:0x3e00
	s_waitcnt lgkmcnt(6)
	v_mfma_f32_32x32x16_bf16 v[2:17], v[148:151], v[172:175], v[2:17]
	s_cmp_le_i32 s7, s6
	s_waitcnt lgkmcnt(4)
	v_mfma_f32_32x32x16_bf16 v[2:17], v[152:155], v[202:205], v[2:17]
	s_waitcnt lgkmcnt(2)
	v_mfma_f32_32x32x16_bf16 v[2:17], v[156:159], v[206:209], v[2:17]
	s_waitcnt lgkmcnt(0)
	v_mfma_f32_32x32x16_bf16 v[2:17], v[160:163], v[224:227], v[2:17]
	s_cbranch_scc1 .LBB0_91
	v_add_u32_e32 v148, 0x4000007b, v197
	v_cmp_gt_u32_e32 vcc, 2.0, v148
	v_add_u32_e32 v148, 0x5b, v197
	s_nop 0
	v_cndmask_b32_e32 v82, v220, v82, vcc
	v_cmp_lt_u32_e32 vcc, s33, v148
	v_add_u32_e32 v148, 0x7a, v197
	s_nop 0
	v_cndmask_b32_e32 v66, v220, v66, vcc
	v_cmp_lt_u32_e32 vcc, s33, v148
	v_add_u32_e32 v148, 0x5a, v197
	s_nop 0
	v_cndmask_b32_e32 v83, v220, v83, vcc
	v_cmp_lt_u32_e32 vcc, s33, v148
	v_add_u32_e32 v148, 0x79, v197
	s_nop 0
	v_cndmask_b32_e32 v67, v220, v67, vcc
	v_cmp_lt_u32_e32 vcc, s33, v148
	v_add_u32_e32 v148, 0x59, v197
	s_nop 0
	v_cndmask_b32_e32 v84, v220, v84, vcc
	v_cmp_lt_u32_e32 vcc, s33, v148
	v_add_u32_e32 v148, 0x78, v197
	s_nop 0
	v_cndmask_b32_e32 v68, v220, v68, vcc
	v_cmp_lt_u32_e32 vcc, s33, v148
	v_add_u32_e32 v148, 0x58, v197
	s_nop 0
	v_cndmask_b32_e32 v85, v220, v85, vcc
	v_cmp_lt_u32_e32 vcc, s33, v148
	v_add_u32_e32 v148, 0x73, v197
	s_nop 0
	v_cndmask_b32_e32 v69, v220, v69, vcc
	v_cmp_lt_u32_e32 vcc, s33, v148
	v_add_u32_e32 v148, 0x53, v197
	s_nop 0
	v_cndmask_b32_e32 v86, v220, v86, vcc
	v_cmp_lt_u32_e32 vcc, s33, v148
	v_add_u32_e32 v148, 0x72, v197
	s_nop 0
	v_cndmask_b32_e32 v70, v220, v70, vcc
	v_cmp_lt_u32_e32 vcc, s33, v148
	v_add_u32_e32 v148, 0x52, v197
	s_nop 0
	v_cndmask_b32_e32 v87, v220, v87, vcc
	v_cmp_lt_u32_e32 vcc, s33, v148
	v_add_u32_e32 v148, 0x71, v197
	s_nop 0
	v_cndmask_b32_e32 v71, v220, v71, vcc
	v_cmp_lt_u32_e32 vcc, s33, v148
	v_add_u32_e32 v148, 0x51, v197
	s_nop 0
	v_cndmask_b32_e32 v88, v220, v88, vcc
	v_cmp_lt_u32_e32 vcc, s33, v148
	v_add_u32_e32 v148, 0x70, v197
	s_nop 0
	v_cndmask_b32_e32 v72, v220, v72, vcc
	v_cmp_lt_u32_e32 vcc, s33, v148
	v_add_u32_e32 v148, 0x50, v197
	s_nop 0
	v_cndmask_b32_e32 v89, v220, v89, vcc
	v_cmp_lt_u32_e32 vcc, s33, v148
	v_add_u32_e32 v148, 0x6b, v197
	s_nop 0
	v_cndmask_b32_e32 v73, v220, v73, vcc
	v_cmp_lt_u32_e32 vcc, s33, v148
	v_add_u32_e32 v148, 0x4b, v197
	s_nop 0
	v_cndmask_b32_e32 v90, v220, v90, vcc
	v_cmp_lt_u32_e32 vcc, s33, v148
	v_add_u32_e32 v148, 0x6a, v197
	s_nop 0
	v_cndmask_b32_e32 v74, v220, v74, vcc
	v_cmp_lt_u32_e32 vcc, s33, v148
	v_add_u32_e32 v148, 0x4a, v197
	s_nop 0
	v_cndmask_b32_e32 v91, v220, v91, vcc
	v_cmp_lt_u32_e32 vcc, s33, v148
	v_add_u32_e32 v148, 0x69, v197
	s_nop 0
	v_cndmask_b32_e32 v75, v220, v75, vcc
	v_cmp_lt_u32_e32 vcc, s33, v148
	v_add_u32_e32 v148, 0x49, v197
	s_nop 0
	v_cndmask_b32_e32 v92, v220, v92, vcc
	v_cmp_lt_u32_e32 vcc, s33, v148
	v_add_u32_e32 v148, 0x68, v197
	s_nop 0
	v_cndmask_b32_e32 v76, v220, v76, vcc
	v_cmp_lt_u32_e32 vcc, s33, v148
	v_add_u32_e32 v148, 0x48, v197
	s_nop 0
	v_cndmask_b32_e32 v93, v220, v93, vcc
	v_cmp_lt_u32_e32 vcc, s33, v148
	v_add_u32_e32 v148, 0x63, v197
	s_nop 0
	v_cndmask_b32_e32 v77, v220, v77, vcc
	v_cmp_lt_u32_e32 vcc, s33, v148
	v_add_u32_e32 v148, 0x43, v197
	s_nop 0
	v_cndmask_b32_e32 v94, v220, v94, vcc
	v_cmp_lt_u32_e32 vcc, s33, v148
	v_add_u32_e32 v148, 0x62, v197
	s_nop 0
	v_cndmask_b32_e32 v78, v220, v78, vcc
	v_cmp_lt_u32_e32 vcc, s33, v148
	v_add_u32_e32 v148, 0x42, v197
	s_nop 0
	v_cndmask_b32_e32 v95, v220, v95, vcc
	v_cmp_lt_u32_e32 vcc, s33, v148
	v_add_u32_e32 v148, 0x61, v197
	s_nop 0
	v_cndmask_b32_e32 v79, v220, v79, vcc
	v_cmp_lt_u32_e32 vcc, s33, v148
	v_add_u32_e32 v148, 0x41, v197
	s_nop 0
	v_cndmask_b32_e32 v96, v220, v96, vcc
	v_cmp_lt_u32_e32 vcc, s33, v148
	v_add_u32_e32 v148, 0x60, v197
	s_nop 0
	v_cndmask_b32_e32 v80, v220, v80, vcc
	v_cmp_lt_u32_e32 vcc, s33, v148
	v_add_u32_e32 v148, 64, v197
	s_nop 0
	v_cndmask_b32_e32 v97, v220, v97, vcc
	v_cmp_lt_u32_e32 vcc, s33, v148
	s_nop 1
	v_cndmask_b32_e32 v81, v220, v81, vcc

; __device__ __forceinline__ void mask_tile(f32x16& p0, f32x16& p1, int dq, unsigned W) {
;     const float NEG = -__builtin_inff();
; #pragma unroll
;     for (int r = 0; r < 16; ++r) {
;         const int c = (r & 3) + 8 * (r >> 2);
;         if ((unsigned)(dq - c) >= W) p0[r] = NEG;
;         if ((unsigned)(dq - c - 32) >= W) p1[r] = NEG;
;     }
; }
; template <int VB>
; __device__ __forceinline__ void pv_tile(f32x16* o, int vb0, bf16x8 pa0, bf16x8 pa1, bf16x8 pa2, bf16x8 pa3) {
;     ...
;     PV_D0(0); PV_D0(1); PV_D0(2); PV_D0(3);
;     ...
; }
.LBB0_97:
	s_nop 0
	s_waitcnt lgkmcnt(2)
	v_mfma_f32_32x32x16_bf16 v[50:65], v[148:151], v[172:175], v[50:65]
	ds_read_b64_tr_b16 v[172:173], v185 offset:0x4200
	ds_read_b64_tr_b16 v[174:175], v185 offset:0x4a00
	v_mfma_f32_32x32x16_bf16 v[50:65], v[152:155], v[206:209], v[50:65]
	ds_read_b64_tr_b16 v[206:207], v185 offset:0x5200
	ds_read_b64_tr_b16 v[208:209], v185 offset:0x5a00
	v_mfma_f32_32x32x16_bf16 v[50:65], v[156:159], v[224:227], v[50:65]
	ds_read_b64_tr_b16 v[224:225], v185 offset:0x6200
	ds_read_b64_tr_b16 v[226:227], v185 offset:0x6a00
	s_waitcnt lgkmcnt(6)
	v_mfma_f32_32x32x16_bf16 v[50:65], v[160:163], v[228:231], v[50:65]
	ds_read_b64_tr_b16 v[228:229], v185 offset:0x7200
	ds_read_b64_tr_b16 v[230:231], v185 offset:0x7a00
	s_waitcnt lgkmcnt(6)
	v_mfma_f32_32x32x16_bf16 v[34:49], v[148:151], v[172:175], v[34:49]
	ds_read_b64_tr_b16 v[172:173], v185 offset:0x4400
	ds_read_b64_tr_b16 v[174:175], v185 offset:0x4c00
	s_waitcnt lgkmcnt(6)
	v_mfma_f32_32x32x16_bf16 v[34:49], v[152:155], v[206:209], v[34:49]
	ds_read_b64_tr_b16 v[206:207], v185 offset:0x5400
	ds_read_b64_tr_b16 v[208:209], v185 offset:0x5c00
	s_waitcnt lgkmcnt(6)
	v_mfma_f32_32x32x16_bf16 v[34:49], v[156:159], v[224:227], v[34:49]
	ds_read_b64_tr_b16 v[224:225], v185 offset:0x6400
	ds_read_b64_tr_b16 v[226:227], v185 offset:0x6c00
	s_waitcnt lgkmcnt(6)
	v_mfma_f32_32x32x16_bf16 v[34:49], v[160:163], v[228:231], v[34:49]
	ds_read_b64_tr_b16 v[228:229], v185 offset:0x7400
	ds_read_b64_tr_b16 v[230:231], v185 offset:0x7c00
	s_waitcnt lgkmcnt(6)
	v_mfma_f32_32x32x16_bf16 v[18:33], v[148:151], v[172:175], v[18:33]
	ds_read_b64_tr_b16 v[172:173], v185 offset:0x4600
	ds_read_b64_tr_b16 v[174:175], v185 offset:0x4e00
	s_waitcnt lgkmcnt(6)
	v_mfma_f32_32x32x16_bf16 v[18:33], v[152:155], v[206:209], v[18:33]
	ds_read_b64_tr_b16 v[206:207], v185 offset:0x5600
	ds_read_b64_tr_b16 v[208:209], v185 offset:0x5e00
	s_waitcnt lgkmcnt(6)
	v_mfma_f32_32x32x16_bf16 v[18:33], v[156:159], v[224:227], v[18:33]
	ds_read_b64_tr_b16 v[224:225], v185 offset:0x6600
	ds_read_b64_tr_b16 v[226:227], v185 offset:0x6e00
	s_waitcnt lgkmcnt(6)
	v_mfma_f32_32x32x16_bf16 v[18:33], v[160:163], v[228:231], v[18:33]
	ds_read_b64_tr_b16 v[228:229], v185 offset:0x7600
	ds_read_b64_tr_b16 v[230:231], v185 offset:0x7e00
	s_waitcnt lgkmcnt(6)
	v_mfma_f32_32x32x16_bf16 v[2:17], v[148:151], v[172:175], v[2:17]
	s_add_i32 s0, s7, 64
	s_cmp_le_i32 s0, s6
	s_waitcnt lgkmcnt(4)
	v_mfma_f32_32x32x16_bf16 v[2:17], v[152:155], v[206:209], v[2:17]
	s_waitcnt lgkmcnt(2)
	v_mfma_f32_32x32x16_bf16 v[2:17], v[156:159], v[224:227], v[2:17]
	s_waitcnt lgkmcnt(0)
	v_mfma_f32_32x32x16_bf16 v[2:17], v[160:163], v[228:231], v[2:17]
	v_subrev_u32_e32 v185, s100, v185
	s_cbranch_scc1 .LBB0_99
	v_add_u32_e32 v148, 0x4000003b, v197
	v_cmp_gt_u32_e32 vcc, 2.0, v148
	v_add_u32_e32 v148, 27, v197
	s_nop 0
	v_cndmask_b32_e32 v82, v220, v82, vcc
	v_cmp_lt_u32_e32 vcc, s33, v148
	v_add_u32_e32 v148, 58, v197
	s_nop 0
	v_cndmask_b32_e32 v66, v220, v66, vcc
	v_cmp_lt_u32_e32 vcc, s33, v148
	v_add_u32_e32 v148, 26, v197
	s_nop 0
	v_cndmask_b32_e32 v83, v220, v83, vcc
	v_cmp_lt_u32_e32 vcc, s33, v148
	v_add_u32_e32 v148, 57, v197
	s_nop 0
	v_cndmask_b32_e32 v67, v220, v67, vcc
	v_cmp_lt_u32_e32 vcc, s33, v148
	v_add_u32_e32 v148, 25, v197
	s_nop 0
	v_cndmask_b32_e32 v84, v220, v84, vcc
	v_cmp_lt_u32_e32 vcc, s33, v148
	v_add_u32_e32 v148, 56, v197
	s_nop 0
	v_cndmask_b32_e32 v68, v220, v68, vcc
	v_cmp_lt_u32_e32 vcc, s33, v148
	v_add_u32_e32 v148, 24, v197
	s_nop 0
	v_cndmask_b32_e32 v85, v220, v85, vcc
	v_cmp_lt_u32_e32 vcc, s33, v148
	v_add_u32_e32 v148, 51, v197
	s_nop 0
	v_cndmask_b32_e32 v69, v220, v69, vcc
	v_cmp_lt_u32_e32 vcc, s33, v148
	v_add_u32_e32 v148, 19, v197
	s_nop 0
	v_cndmask_b32_e32 v86, v220, v86, vcc
	v_cmp_lt_u32_e32 vcc, s33, v148
	v_add_u32_e32 v148, 50, v197
	s_nop 0
	v_cndmask_b32_e32 v70, v220, v70, vcc
	v_cmp_lt_u32_e32 vcc, s33, v148
	v_add_u32_e32 v148, 18, v197
	s_nop 0
	v_cndmask_b32_e32 v87, v220, v87, vcc
	v_cmp_lt_u32_e32 vcc, s33, v148
	v_add_u32_e32 v148, 49, v197
	s_nop 0
	v_cndmask_b32_e32 v71, v220, v71, vcc
	v_cmp_lt_u32_e32 vcc, s33, v148
	v_add_u32_e32 v148, 17, v197
	s_nop 0
	v_cndmask_b32_e32 v88, v220, v88, vcc
	v_cmp_lt_u32_e32 vcc, s33, v148
	v_add_u32_e32 v148, 48, v197
	s_nop 0
	v_cndmask_b32_e32 v72, v220, v72, vcc
	v_cmp_lt_u32_e32 vcc, s33, v148
	v_add_u32_e32 v148, 16, v197
	s_nop 0
	v_cndmask_b32_e32 v89, v220, v89, vcc
	v_cmp_lt_u32_e32 vcc, s33, v148
	v_add_u32_e32 v148, 43, v197
	s_nop 0
	v_cndmask_b32_e32 v73, v220, v73, vcc
	v_cmp_lt_u32_e32 vcc, s33, v148
	v_add_u32_e32 v148, 11, v197
	s_nop 0
	v_cndmask_b32_e32 v90, v220, v90, vcc
	v_cmp_lt_u32_e32 vcc, s33, v148
	v_add_u32_e32 v148, 42, v197
	s_nop 0
	v_cndmask_b32_e32 v74, v220, v74, vcc
	v_cmp_lt_u32_e32 vcc, s33, v148
	v_add_u32_e32 v148, 10, v197
	s_nop 0
	v_cndmask_b32_e32 v91, v220, v91, vcc
	v_cmp_lt_u32_e32 vcc, s33, v148
	v_add_u32_e32 v148, 41, v197
	s_nop 0
	v_cndmask_b32_e32 v75, v220, v75, vcc
	v_cmp_lt_u32_e32 vcc, s33, v148
	v_add_u32_e32 v148, 9, v197
	s_nop 0
	v_cndmask_b32_e32 v92, v220, v92, vcc
	v_cmp_lt_u32_e32 vcc, s33, v148
	v_add_u32_e32 v148, 40, v197
	s_nop 0
	v_cndmask_b32_e32 v76, v220, v76, vcc
	v_cmp_lt_u32_e32 vcc, s33, v148
	v_add_u32_e32 v148, 8, v197
	s_nop 0
	v_cndmask_b32_e32 v93, v220, v93, vcc
	v_cmp_lt_u32_e32 vcc, s33, v148
	v_add_u32_e32 v148, 35, v197
	s_nop 0
	v_cndmask_b32_e32 v77, v220, v77, vcc
	v_cmp_lt_u32_e32 vcc, s33, v148
	v_add_u32_e32 v148, 3, v197
	s_nop 0
	v_cndmask_b32_e32 v94, v220, v94, vcc
	v_cmp_lt_u32_e32 vcc, s33, v148
	v_add_u32_e32 v148, 34, v197
	s_nop 0
	v_cndmask_b32_e32 v78, v220, v78, vcc
	v_cmp_lt_u32_e32 vcc, s33, v148
	v_add_u32_e32 v148, 2, v197
	s_nop 0
	v_cndmask_b32_e32 v95, v220, v95, vcc
	v_cmp_lt_u32_e32 vcc, s33, v148
	v_add_u32_e32 v148, 33, v197
	s_nop 0
	v_cndmask_b32_e32 v79, v220, v79, vcc
	v_cmp_lt_u32_e32 vcc, s33, v148
	v_add_u32_e32 v148, 1, v197
	s_nop 0
	v_cndmask_b32_e32 v96, v220, v96, vcc
	v_cmp_lt_u32_e32 vcc, s33, v148
	v_add_u32_e32 v148, 32, v197
	s_nop 0
	v_cndmask_b32_e32 v80, v220, v80, vcc
	v_cmp_lt_u32_e32 vcc, s33, v148
	s_nop 1
	v_cndmask_b32_e32 v97, v220, v97, vcc
	v_cmp_lt_u32_e32 vcc, s33, v197
	s_nop 1
	v_cndmask_b32_e32 v81, v220, v81, vcc
